# layer-0 out phase: 24 context-chunk units moved after the phase barrier onto WGs 232-255 (overlap gemm-out), context gemm tiles wait on a device-scope counter
# speedup vs baseline: 1.0138x; 1.0072x over previous
.LBB0_689:
	s_movk_i32 s8, 0x108
	s_cmpk_eq_i32 s36, 0x100
	s_cselect_b32 s8, 0x100, s8
.LBB0_690:
	s_cmpk_eq_i32 s8, 0x100
	s_cselect_b64 s[100:101], -1, 0
	s_mul_i32 s9, s8, 3
	v_readlane_b32 s0, v255, 0
	s_cmp_ge_i32 s0, s9
	s_mov_b32 s52, 0x10800
	s_mov_b32 s53, 0x8100
	s_mov_b32 s59, 0x3195000
	s_cbranch_scc1 .LBB0_1159
	v_cvt_f32_u32_e32 v0, s8
	v_readlane_b32 s0, v255, 25
	s_sub_i32 s4, 0, s8
	v_readlane_b32 s1, v255, 26
	v_rcp_iflag_f32_e32 v0, v0
	s_mov_b32 s2, s0
	s_lshl_b32 s48, s0, 8
	s_lshl_b32 s10, s0, 10
	v_mul_f32_e32 v0, 0x4f7ffffe, v0
	v_cvt_u32_f32_e32 v0, v0
	s_lshl_b32 s24, s0, 1
	s_lshl_b32 s0, s0, 9
	s_mov_b32 s1, s49
	v_readfirstlane_b32 s5, v0
	s_mul_i32 s4, s4, s5
	s_lshl_b32 s14, s2, 11
	s_lshl_b32 s25, s2, 3
	s_lshl_b32 s26, s2, 2
	s_lshl_b32 s27, s2, 12
	s_lshl_b32 s2, s2, 6
	s_mov_b32 s3, s49
	s_mul_hi_u32 s4, s5, s4
	s_mov_b32 s11, s49
	s_mov_b32 s15, s49
	s_add_i32 s28, s5, s4
	s_lshl_b64 s[16:17], s[2:3], 2
	s_lshl_b64 s[18:19], s[0:1], 2
	v_readlane_b32 s29, v255, 0
	s_branch .LBB0_694

.LBB0_694:
	s_abs_i32 s1, s29
	s_mul_hi_u32 s2, s1, s28
	s_mul_i32 s3, s2, s8
	s_sub_i32 s1, s1, s3
	s_ashr_i32 s0, s29, 31
	s_add_i32 s3, s2, 1
	s_sub_i32 s4, s1, s8
	s_cmp_ge_u32 s1, s8
	s_cselect_b32 s2, s3, s2
	s_cselect_b32 s1, s4, s1
	s_add_i32 s3, s2, 1
	s_cmp_ge_u32 s1, s8
	s_cselect_b32 s1, s3, s2
	s_xor_b32 s1, s1, s0
	s_sub_i32 s34, s1, s0
	s_mul_i32 s0, s34, s8
	s_sub_i32 s2, s29, s0
	s_mov_b64 s[0:1], -1
	s_and_b64 vcc, exec, s[100:101]
	s_cbranch_vccnz .LBB0_703
	s_andn2_b64 vcc, exec, s[0:1]
	s_mul_hi_i32 s3, s2, 0x3e0f83e1
	s_cbranch_vccz .LBB0_704
.LBB0_696:
	s_mov_b64 s[0:1], -1
	s_and_b64 vcc, exec, s[100:101]
	s_cbranch_vccnz .LBB0_705

.LBB0_704:
	s_lshr_b32 s0, s3, 31
	s_ashr_i32 s1, s3, 5
	s_add_i32 s30, s1, s0
	s_mov_b64 s[0:1], -1
	s_and_b64 vcc, exec, s[100:101]
	s_cbranch_vccz .LBB0_697

.LBB0_1212:
	s_or_b64 exec, exec, s[0:1]
	s_waitcnt lgkmcnt(0)
	s_barrier
	v_readlane_b32 s0, v255, 25
	v_readlane_b32 s1, v255, 0
	s_cmp_lg_u32 s0, 0
	s_cbranch_scc1 .Lcx_mark7
	s_cmpk_lg_i32 s36, 0x100
	s_cbranch_scc1 .Lcx_mark7
	s_sub_i32 s1, s1, 232
	s_cmp_lt_u32 s1, 24
	s_cbranch_scc0 .Lcx_mark7
	s_lshr_b32 s2, s1, 3
	s_mulk_i32 s2, 0x108
	s_bfe_u32 s3, s1, 0x10002
	s_mulk_i32 s3, 0x84
	s_and_b32 s1, s1, 3
	s_add_i32 s2, s2, s3
	s_add_i32 s29, s2, s1
	s_movk_i32 s8, 0x108
	s_mov_b32 s52, 0x10800
	s_mov_b32 s53, 0x8100
	s_mov_b32 s59, 0x3195000
	v_cvt_f32_u32_e32 v0, s8
	v_readlane_b32 s0, v255, 25
	s_sub_i32 s4, 0, s8
	v_readlane_b32 s1, v255, 26
	v_rcp_iflag_f32_e32 v0, v0
	s_mov_b32 s2, s0
	s_lshl_b32 s48, s0, 8
	s_lshl_b32 s10, s0, 10
	v_mul_f32_e32 v0, 0x4f7ffffe, v0
	v_cvt_u32_f32_e32 v0, v0
	s_lshl_b32 s24, s0, 1
	s_lshl_b32 s0, s0, 9
	s_mov_b32 s1, s49
	v_readfirstlane_b32 s5, v0
	s_mul_i32 s4, s4, s5
	s_lshl_b32 s14, s2, 11
	s_lshl_b32 s25, s2, 3
	s_lshl_b32 s26, s2, 2
	s_lshl_b32 s27, s2, 12
	s_lshl_b32 s2, s2, 6
	s_mov_b32 s3, s49
	s_mul_hi_u32 s4, s5, s4
	s_mov_b32 s11, s49
	s_mov_b32 s15, s49
	s_add_i32 s28, s5, s4
	s_lshl_b64 s[16:17], s[2:3], 2
	s_lshl_b64 s[18:19], s[0:1], 2
	s_mov_b32 s9, 0
	s_mov_b64 s[100:101], 0
	s_branch .LBB0_694
.Lcx_exit:
	s_cmp_eq_u32 s9, 0
	s_cbranch_scc1 .Lcx_done
	s_branch .LBB0_1159
.Lcx_done:
	s_waitcnt vmcnt(0) lgkmcnt(0)
	s_barrier
	v_cmp_eq_u32_e32 vcc, 0, v206
	s_and_saveexec_b64 s[0:1], vcc
	s_cbranch_execz .Lcx_sigskip
	buffer_wbl2 sc1
	s_waitcnt vmcnt(0)
	ds_read_b64 v[0:1], v129 offset:232
	v_mov_b32_e32 v2, 1
	s_waitcnt lgkmcnt(0)
	v_add_co_u32_e32 v0, vcc, 0xe643100, v0
	s_nop 1
	v_addc_co_u32_e32 v1, vcc, 0, v1, vcc
	global_atomic_add v[0:1], v2, off
	s_waitcnt vmcnt(0)
.Lcx_sigskip:
	s_or_b64 exec, exec, s[0:1]
	s_mov_b64 s[28:29], 0x98b5000
.Lcx_mark7:
	ds_read_b64 v[0:1], v129 offset:232
	v_readlane_b32 s0, v255, 25
	v_readlane_b32 s1, v255, 26
	s_mov_b32 s1, s49
	s_lshl_b64 s[0:1], s[0:1], 21
	s_waitcnt lgkmcnt(0)
	v_lshl_add_u64 v[2:3], v[0:1], 0, s[0:1]
	v_readlane_b32 s0, v255, 23
	v_readlane_b32 s1, v255, 24
	s_and_b64 s[0:1], exec, s[0:1]
	s_cselect_b32 s10, 0x42, 64
	v_readlane_b32 s0, v255, 5
	v_mov_b32_e32 v4, v206
	s_mul_i32 s15, s10, s0
	s_lshl_b32 s11, s10, 3
	s_add_i32 s0, s15, s10
	v_lshlrev_b32_e32 v8, 4, v4
	s_min_u32 s14, s11, s0
	v_and_b32_e32 v128, 0x70, v8
	v_readlane_b32 s0, v255, 6
	s_add_i32 s15, s15, s0
	v_lshl_add_u64 v[0:1], v[0:1], 0, v[128:129]
	s_mov_b64 s[0:1], 0x1095000
	v_lshl_add_u64 v[178:179], v[0:1], 0, s[0:1]
	v_lshl_add_u64 v[0:1], v[2:3], 0, v[128:129]
	s_mov_b64 s[0:1], 0xc80000
	v_lshl_add_u64 v[180:181], v[0:1], 0, s[0:1]
	v_ashrrev_i32_e32 v1, 1, v4
	v_and_b32_e32 v6, 31, v4
	v_and_b32_e32 v202, 0xffffffc0, v1
	v_bfe_u32 v7, v4, 5, 1
	s_movk_i32 s0, 0x90
	v_or_b32_e32 v1, v202, v6
	v_mul_lo_u32 v1, v1, s0
	v_lshlrev_b32_e32 v2, 4, v7
	v_ashrrev_i32_e32 v200, 3, v4
	v_add3_u32 v203, s57, v1, v2
	v_and_b32_e32 v1, 0x5f, v4
	v_mul_lo_u32 v0, v200, s0
	v_mul_u32_u24_e32 v1, 0x90, v1
	v_readlane_b32 s0, v255, 15
	v_ashrrev_i32_e32 v5, 6, v4
	v_add3_u32 v201, s57, v128, v0
	v_add3_u32 v234, s0, v128, v0
	v_add3_u32 v235, s0, v1, v2
	s_movk_i32 s0, 0x4400
	v_add3_u32 v204, s57, v1, v2
	v_mul_lo_u32 v0, v5, s0
	v_lshlrev_b32_e32 v2, 2, v4
	v_add_u32_e32 v0, 0x100, v0
	v_lshlrev_b32_e32 v1, 2, v6
	v_and_b32_e32 v2, 60, v2
	v_bfe_u32 v237, v4, 4, 2
	v_mul_u32_u24_e32 v3, 0x440, v7
	v_and_or_b32 v236, v4, 64, v2
	v_lshl_add_u32 v2, v2, 2, v0
	v_add3_u32 v238, v0, v1, v3
	v_mul_u32_u24_e32 v0, 0x110, v237
	v_mov_b32_e32 v210, 0xc0c0
	v_mov_b32_e32 v209, 0xacac
	v_mov_b32_e32 v208, v252
	v_cmp_lt_i32_e64 s[2:3], 3, v5
	v_add_u32_e32 v205, 0xd800, v201
	v_or_b32_e32 v239, 4, v237
	v_or_b32_e32 v240, 8, v237
	v_or_b32_e32 v241, 12, v237
	v_or_b32_e32 v242, 16, v237
	v_or_b32_e32 v243, 20, v237
	v_or_b32_e32 v244, 24, v237
	v_or_b32_e32 v245, 28, v237
	v_or_b32_e32 v246, 32, v237
	v_or_b32_e32 v247, 36, v237
	v_or_b32_e32 v248, 40, v237
	v_or_b32_e32 v249, 44, v237
	v_or_b32_e32 v250, 48, v237
	v_or_b32_e32 v251, 52, v237
	v_or_b32_e32 v252, 56, v237
	v_or_b32_e32 v253, 60, v237
	s_mov_b32 s16, 0
	v_add_u32_e32 v254, v2, v0
	s_branch .LBB0_1216

.LBB0_1224:
	s_and_b64 vcc, exec, s[0:1]
	s_cbranch_vccz .LBB0_1215
	s_cmp_lt_u32 s17, 64
	s_cbranch_scc1 .Lcx_nowait
	s_cmpk_lg_i32 s36, 0x100
	s_cbranch_scc1 .Lcx_nowait
	ds_read_b64 v[0:1], v129 offset:232
	s_mov_b32 s8, 0
	s_waitcnt lgkmcnt(0)
	v_readfirstlane_b32 s4, v0
	v_readfirstlane_b32 s5, v1
	s_add_u32 s4, s4, 0xe643100
	s_addc_u32 s5, s5, 0
	s_nop 4
.Lcx_wait:
	global_load_dword v0, v129, s[4:5] sc1
	s_add_i32 s8, s8, 1
	s_waitcnt vmcnt(0)
	v_readfirstlane_b32 s7, v0
	s_cmp_ge_u32 s7, 24
	s_cbranch_scc1 .Lcx_go
	s_cmp_gt_u32 s8, 0x8000
	s_cbranch_scc1 .Lcx_go
	s_sleep 2
	s_branch .Lcx_wait

.Lcx_nowait:
	s_lshl_b32 s8, s17, 8
	v_add_u32_e32 v0, s8, v200
	v_ashrrev_i32_e32 v1, 31, v0
	s_lshl_b32 s9, s18, 7
	v_lshlrev_b64 v[0:1], 11, v[0:1]
	v_lshl_add_u64 v[182:183], v[178:179], 0, v[0:1]
	v_add_u32_e32 v0, s9, v200
	v_ashrrev_i32_e32 v1, 31, v0
	v_lshlrev_b64 v[0:1], 11, v[0:1]
	v_lshl_add_u64 v[184:185], v[180:181], 0, v[0:1]
	v_add_co_u32_e32 v0, vcc, 0x20000, v182
	s_mov_b64 s[4:5], 0x40000
	s_nop 0
	v_addc_co_u32_e32 v1, vcc, 0, v183, vcc
	v_add_co_u32_e32 v2, vcc, 0x40000, v182
	s_mov_b64 s[0:1], 0x20000
	s_nop 0
	v_addc_co_u32_e32 v3, vcc, 0, v183, vcc
	global_load_dwordx4 v[112:115], v[0:1], off
	global_load_dwordx4 v[116:119], v[2:3], off
	v_add_co_u32_e32 v0, vcc, 0x60000, v182
	global_load_dwordx4 v[120:123], v[182:183], off
	global_load_dwordx4 v[124:127], v[184:185], off
	v_addc_co_u32_e32 v1, vcc, 0, v183, vcc
	v_add_co_u32_e32 v2, vcc, 0x20000, v184
	v_lshl_add_u64 v[188:189], v[182:183], 0, s[4:5]
	s_nop 0
	v_addc_co_u32_e32 v3, vcc, 0, v185, vcc
	global_load_dwordx4 v[130:133], v[0:1], off
	global_load_dwordx4 v[134:137], v[2:3], off
	s_mov_b64 s[4:5], 0x60000
	v_lshl_add_u64 v[186:187], v[182:183], 0, s[0:1]
	v_lshl_add_u64 v[190:191], v[182:183], 0, s[4:5]
	v_lshl_add_u64 v[192:193], v[184:185], 0, s[0:1]
	s_and_saveexec_b64 s[0:1], s[2:3]
	s_xor_b64 s[0:1], exec, s[0:1]
	s_cbranch_execz .LBB0_1231
	v_add_co_u32_e32 v0, vcc, 0x20000, v182
	s_mov_b32 s6, 0
	s_nop 0
	v_addc_co_u32_e32 v1, vcc, 0, v183, vcc
	v_add_co_u32_e32 v2, vcc, 0x40000, v182
	s_nop 1
	v_addc_co_u32_e32 v3, vcc, 0, v183, vcc
	v_add_co_u32_e32 v4, vcc, 0x60000, v182
	s_nop 1
	v_addc_co_u32_e32 v5, vcc, 0, v183, vcc
	v_add_co_u32_e32 v6, vcc, s58, v184
	s_nop 1
	v_addc_co_u32_e32 v7, vcc, 0, v185, vcc
	global_load_dwordx4 v[64:67], v[182:183], off offset:128
	global_load_dwordx4 v[68:71], v[0:1], off offset:128
	global_load_dwordx4 v[80:83], v[2:3], off offset:128
	global_load_dwordx4 v[84:87], v[4:5], off offset:128
	global_load_dwordx4 v[96:99], v[184:185], off offset:128
	global_load_dwordx4 v[100:103], v[6:7], off offset:128
	global_load_dwordx4 v[72:75], v[182:183], off offset:256
	global_load_dwordx4 v[76:79], v[0:1], off offset:256
	global_load_dwordx4 v[88:91], v[2:3], off offset:256
	global_load_dwordx4 v[92:95], v[4:5], off offset:256
	global_load_dwordx4 v[104:107], v[184:185], off offset:256
	global_load_dwordx4 v[108:111], v[6:7], off offset:256
	v_mov_b32_e32 v0, 0
	v_mov_b32_e32 v1, v0
	v_mov_b32_e32 v2, v0
	v_mov_b32_e32 v3, v0
	v_mov_b32_e32 v4, v0
	v_mov_b32_e32 v5, v0
	v_mov_b32_e32 v6, v0
	v_mov_b32_e32 v7, v0
	v_mov_b32_e32 v8, v0
	v_mov_b32_e32 v9, v0
	v_mov_b32_e32 v10, v0
	v_mov_b32_e32 v11, v0
	v_mov_b32_e32 v12, v0
	v_mov_b32_e32 v13, v0
	v_mov_b32_e32 v14, v0
	v_mov_b32_e32 v15, v0
	v_mov_b32_e32 v16, v0
	v_mov_b32_e32 v17, v0
	v_mov_b32_e32 v18, v0
	v_mov_b32_e32 v19, v0
	v_mov_b32_e32 v20, v0
	v_mov_b32_e32 v21, v0
	v_mov_b32_e32 v22, v0
	v_mov_b32_e32 v23, v0
	v_mov_b32_e32 v24, v0
	v_mov_b32_e32 v25, v0
	v_mov_b32_e32 v26, v0
	v_mov_b32_e32 v27, v0
	v_mov_b32_e32 v28, v0
	v_mov_b32_e32 v29, v0
	v_mov_b32_e32 v30, v0
	v_mov_b32_e32 v31, v0
	v_mov_b32_e32 v32, v0
	v_mov_b32_e32 v33, v0
	v_mov_b32_e32 v34, v0
	v_mov_b32_e32 v35, v0
	v_mov_b32_e32 v36, v0
	v_mov_b32_e32 v37, v0
	v_mov_b32_e32 v38, v0
	v_mov_b32_e32 v39, v0
	v_mov_b32_e32 v40, v0
	v_mov_b32_e32 v41, v0
	v_mov_b32_e32 v42, v0
	v_mov_b32_e32 v43, v0
	v_mov_b32_e32 v44, v0
	v_mov_b32_e32 v45, v0
	v_mov_b32_e32 v46, v0
	v_mov_b32_e32 v47, v0
	v_mov_b32_e32 v48, v0
	v_mov_b32_e32 v49, v0
	v_mov_b32_e32 v50, v0
	v_mov_b32_e32 v51, v0
	v_mov_b32_e32 v52, v0
	v_mov_b32_e32 v53, v0
	v_mov_b32_e32 v54, v0
	v_mov_b32_e32 v55, v0
	v_mov_b32_e32 v56, v0
	v_mov_b32_e32 v57, v0
	v_mov_b32_e32 v58, v0
	v_mov_b32_e32 v59, v0
	v_mov_b32_e32 v60, v0
	v_mov_b32_e32 v61, v0
	v_mov_b32_e32 v62, v0
	v_mov_b32_e32 v63, v0
	s_waitcnt vmcnt(15)
	ds_write_b128 v201, v[120:123]
	ds_write_b128 v201, v[112:115] offset:9216
	ds_write_b128 v201, v[116:119] offset:18432
	s_waitcnt vmcnt(13)
	ds_write_b128 v201, v[130:133] offset:27648
	ds_write_b128 v201, v[124:127] offset:36864
	s_waitcnt vmcnt(12)
	ds_write_b128 v201, v[134:137] offset:46080
	s_waitcnt lgkmcnt(0)
	s_barrier
	s_branch .LBB0_1228
